# S5 pass C split, half deferral: only waves 4-7 of the RWKV workgroups move their second item to phase 4
# baseline (speedup 1.0000x reference)
.LBB0_857:
	v_ashrrev_i32_e32 v0, 6, v45
	v_lshl_add_u32 v33, s2, 3, v0
	s_waitcnt lgkmcnt(0)
	s_mov_b32 s4, s54
	s_movk_i32 s99, 0x1000
	v_readfirstlane_b32 s4, v0
	s_cmp_eq_u32 s53, 4
	s_cbranch_scc0 .Ls5_p3
	v_add_u32_e32 v33, 0x800, v33
	s_cmp_gt_u32 s4, 3
	s_cbranch_scc1 .Ls5_lim
	s_movk_i32 s99, 0
	s_branch .Ls5_lim
.Ls5_p3:
	s_cmpk_gt_u32 s73, 0xdf
	s_cbranch_scc1 .Ls5_lim
	s_cmp_lt_u32 s4, 4
	s_cbranch_scc1 .Ls5_lim
	s_movk_i32 s99, 0x800
.Ls5_lim:
	s_mov_b32 s4, s54
	v_cmp_gt_i32_e32 vcc, s99, v33
	s_and_saveexec_b64 s[12:13], vcc
	s_cbranch_execz .LBB0_884
	v_bfe_u32 v11, v44, 2, 4
	v_and_b32_e32 v13, 12, v11
	v_or_b32_e32 v17, 1, v13
	v_lshlrev_b32_e32 v18, 6, v17
	v_lshlrev_b32_e32 v94, 9, v17
	v_or_b32_e32 v17, 2, v13
	v_lshlrev_b32_e32 v19, 6, v17
	v_lshlrev_b32_e32 v95, 9, v17
	v_or_b32_e32 v17, 3, v11
	v_lshlrev_b32_e32 v20, 6, v17
	v_lshlrev_b32_e32 v96, 9, v17
	v_or_b32_e32 v17, 16, v13
	v_lshlrev_b32_e32 v21, 6, v17
	v_lshlrev_b32_e32 v97, 9, v17
	v_or_b32_e32 v17, 17, v13
	v_lshlrev_b32_e32 v22, 6, v17
	v_lshlrev_b32_e32 v98, 9, v17
	v_or_b32_e32 v17, 18, v13
	v_lshlrev_b32_e32 v23, 6, v17
	v_lshlrev_b32_e32 v99, 9, v17
	v_or_b32_e32 v17, 19, v11
	v_lshlrev_b32_e32 v24, 6, v17
	v_lshlrev_b32_e32 v100, 9, v17
	v_or_b32_e32 v17, 32, v13
	v_lshlrev_b32_e32 v25, 6, v17
	v_lshlrev_b32_e32 v101, 9, v17
	v_or_b32_e32 v17, 33, v13
	v_lshlrev_b32_e32 v26, 6, v17
	v_lshlrev_b32_e32 v102, 9, v17
	v_or_b32_e32 v17, 34, v13
	s_movk_i32 s2, 0x2200
	v_lshlrev_b32_e32 v27, 6, v17
	v_lshlrev_b32_e32 v103, 9, v17
	v_or_b32_e32 v17, 35, v11
	v_mul_lo_u32 v1, v0, s2
	v_lshlrev_b32_e32 v3, 12, v0
	v_readlane_b32 s2, v255, 9
	v_bfe_u32 v9, v44, 1, 5
	v_lshlrev_b32_e32 v28, 6, v17
	v_lshlrev_b32_e32 v104, 9, v17
	v_or_b32_e32 v17, 48, v13
	v_and_b32_e32 v35, 63, v44
	v_add_u32_e32 v1, 0, v1
	v_add_u32_e32 v5, s2, v3
	v_and_b32_e32 v2, 15, v44
	v_and_b32_e32 v4, 24, v9
	v_lshlrev_b32_e32 v16, 6, v13
	v_lshlrev_b32_e32 v93, 9, v13
	v_lshlrev_b32_e32 v29, 6, v17
	v_lshlrev_b32_e32 v105, 9, v17
	v_or_b32_e32 v17, 49, v13
	v_or_b32_e32 v13, 50, v13
	v_or_b32_e32 v11, 51, v11
	s_lshl_b32 s19, s4, 3
	v_mul_u32_u24_e32 v0, 0x1a00, v35
	v_lshlrev_b32_e32 v7, 6, v35
	v_or_b32_e32 v6, 7, v9
	v_or_b32_e32 v8, 39, v9
	v_or_b32_e32 v10, 0x47, v9
	v_or_b32_e32 v12, 0x67, v9
	v_readlane_b32 s4, v255, 27
	v_lshl_add_u32 v9, v4, 1, v1
	v_lshl_add_u32 v14, v2, 2, v5
	v_mul_u32_u24_e32 v15, 0x110, v2
	v_lshlrev_b32_e32 v30, 6, v17
	v_lshlrev_b32_e32 v106, 9, v17
	v_lshlrev_b32_e32 v17, 6, v13
	v_lshlrev_b32_e32 v107, 9, v13
	v_lshlrev_b32_e32 v13, 6, v11
	v_lshlrev_b32_e32 v32, 4, v35
	v_lshlrev_b32_e32 v34, 6, v2
	v_or_b32_e32 v92, s4, v2
	v_lshlrev_b32_e32 v108, 9, v11
	v_lshl_add_u32 v109, v35, 1, v1
	v_lshlrev_b32_e32 v36, 3, v35
	v_mov_b32_e32 v37, v169
	v_add_u32_e32 v110, 0, v3
	s_mov_b64 s[22:23], 0
	v_lshlrev_b32_e32 v38, 2, v0
	v_add_u32_e32 v111, v5, v7
	v_lshlrev_b32_e32 v40, 2, v4
	v_lshlrev_b32_e32 v42, 2, v6
	v_lshlrev_b32_e32 v44, 2, v8
	v_lshlrev_b32_e32 v46, 2, v10
	v_lshlrev_b32_e32 v48, 2, v12
	v_lshlrev_b32_e32 v50, 1, v2
	v_add_u32_e32 v112, v14, v16
	v_add_u32_e32 v113, v14, v18
	v_add_u32_e32 v114, v14, v19
	v_add_u32_e32 v115, v14, v20
	v_add_u32_e32 v116, v14, v21
	v_add_u32_e32 v117, v14, v22
	v_add_u32_e32 v118, v14, v23
	v_add_u32_e32 v119, v14, v24
	v_add_u32_e32 v120, v14, v25
	v_add_u32_e32 v121, v14, v26
	v_add_u32_e32 v122, v14, v27
	v_add_u32_e32 v123, v14, v28
	v_add_u32_e32 v124, v14, v29
	v_add_u32_e32 v125, v14, v30
	v_add_u32_e32 v126, v14, v17
	v_add_u32_e32 v127, v14, v13
	v_add_u32_e32 v128, v9, v15
	v_readlane_b32 s5, v255, 28
